# v52 + P4 K-loop: A-fragment LDS reads hoisted into the preceding MFMA segment (double-buffered At in v220-251), DMA completion waits before each closing barrier
# speedup vs baseline: 1.0091x; 1.0082x over previous
.LBB0_484:
	s_ashr_i32 s17, s16, 31
	s_lshl_b64 s[18:19], s[16:17], 19
	s_add_u32 s18, s8, s18
	s_addc_u32 s19, s9, s19
	s_ashr_i32 s11, s10, 31
	s_lshl_b64 s[20:21], s[10:11], 19
	s_add_u32 s20, s56, s20
	ds_read_b128 v[0:3], v150
	ds_read_b128 v[4:7], v150 offset:1024
	s_waitcnt lgkmcnt(6)
	ds_read_b128 v[8:11], v150 offset:2048
	s_waitcnt lgkmcnt(3)
	ds_read_b128 v[12:15], v150 offset:3072
	ds_read_b128 v[16:19], v151
	ds_read_b128 v[20:23], v151 offset:1024
	ds_read_b128 v[24:27], v151 offset:2048
	ds_read_b128 v[28:31], v151 offset:3072
	s_addc_u32 s21, s57, s21
	s_add_u32 s38, s40, 0x1000
	s_addc_u32 s39, s41, 0
	s_add_u32 s42, s40, 0x1800
	s_addc_u32 s43, s41, 0
	s_and_b64 s[44:45], s[4:5], exec
	s_cselect_b32 s1, s19, s41
	s_cselect_b32 s11, s18, s40
	s_add_u32 s44, s36, 0x1000
	s_addc_u32 s45, s37, 0
	s_and_b64 s[46:47], s[4:5], exec
	s_cselect_b32 s17, s21, s37
	s_cselect_b32 s76, s20, s36
	ds_read_b128 v[32:35], v152
	ds_read_b128 v[36:39], v152 offset:1024
	ds_read_b128 v[40:43], v152 offset:2048
	ds_read_b128 v[44:47], v152 offset:3072
	ds_read_b128 v[48:51], v152 offset:4096
	ds_read_b128 v[52:55], v152 offset:5120
	ds_read_b128 v[56:59], v152 offset:6144
	ds_read_b128 v[60:63], v152 offset:7168
	s_add_u32 s46, s40, 0x40800
	s_addc_u32 s47, s41, 0
	s_mov_b32 m0, s71
	s_nop 0
	global_load_lds_dwordx4 v144, s[46:47]
	s_mov_b32 m0, s72
	s_nop 0
	global_load_lds_dwordx4 v146, s[46:47]
	s_waitcnt vmcnt(8)
	s_waitcnt lgkmcnt(0)
	s_barrier
	s_setprio 1
	s_waitcnt lgkmcnt(7)
	v_mfma_f32_16x16x32_bf16 v[64:67], v[0:3], v[32:35], 0
	v_mfma_f32_16x16x32_bf16 v[68:71], v[8:11], v[32:35], 0
	s_waitcnt lgkmcnt(5)
	v_mfma_f32_16x16x32_bf16 v[72:75], v[0:3], v[40:43], 0
	v_mfma_f32_16x16x32_bf16 v[76:79], v[8:11], v[40:43], 0
	s_waitcnt lgkmcnt(3)
	v_mfma_f32_16x16x32_bf16 v[80:83], v[0:3], v[48:51], 0
	v_mfma_f32_16x16x32_bf16 v[84:87], v[8:11], v[48:51], 0
	s_waitcnt lgkmcnt(1)
	v_mfma_f32_16x16x32_bf16 v[92:95], v[0:3], v[56:59], 0
	v_mfma_f32_16x16x32_bf16 v[100:103], v[8:11], v[56:59], 0
	v_mfma_f32_16x16x32_bf16 v[64:67], v[4:7], v[36:39], v[64:67]
	v_mfma_f32_16x16x32_bf16 v[68:71], v[12:15], v[36:39], v[68:71]
	v_mfma_f32_16x16x32_bf16 v[72:75], v[4:7], v[44:47], v[72:75]
	v_mfma_f32_16x16x32_bf16 v[76:79], v[12:15], v[44:47], v[76:79]
	v_mfma_f32_16x16x32_bf16 v[80:83], v[4:7], v[52:55], v[80:83]
	v_mfma_f32_16x16x32_bf16 v[84:87], v[12:15], v[52:55], v[84:87]
	s_waitcnt lgkmcnt(0)
	v_mfma_f32_16x16x32_bf16 v[92:95], v[4:7], v[60:63], v[92:95]
	v_mfma_f32_16x16x32_bf16 v[100:103], v[12:15], v[60:63], v[100:103]
	s_setprio 0
	s_setprio 1
	v_mfma_f32_16x16x32_bf16 v[108:111], v[16:19], v[32:35], 0
	v_mfma_f32_16x16x32_bf16 v[116:119], v[24:27], v[32:35], 0
	v_mfma_f32_16x16x32_bf16 v[32:35], v[16:19], v[40:43], 0
	v_mfma_f32_16x16x32_bf16 v[136:139], v[24:27], v[40:43], 0
	v_mfma_f32_16x16x32_bf16 v[40:43], v[16:19], v[48:51], 0
	v_mfma_f32_16x16x32_bf16 v[140:143], v[24:27], v[48:51], 0
	v_mfma_f32_16x16x32_bf16 v[48:51], v[16:19], v[56:59], 0
	v_mfma_f32_16x16x32_bf16 v[156:159], v[24:27], v[56:59], 0
	s_nop 0
	v_mfma_f32_16x16x32_bf16 v[108:111], v[20:23], v[36:39], v[108:111]
	v_mfma_f32_16x16x32_bf16 v[116:119], v[28:31], v[36:39], v[116:119]
	v_mfma_f32_16x16x32_bf16 v[32:35], v[20:23], v[44:47], v[32:35]
	v_mfma_f32_16x16x32_bf16 v[136:139], v[28:31], v[44:47], v[136:139]
	v_mfma_f32_16x16x32_bf16 v[40:43], v[20:23], v[52:55], v[40:43]
	v_mfma_f32_16x16x32_bf16 v[140:143], v[28:31], v[52:55], v[140:143]
	v_mfma_f32_16x16x32_bf16 v[48:51], v[20:23], v[60:63], v[48:51]
	v_mfma_f32_16x16x32_bf16 v[156:159], v[28:31], v[60:63], v[156:159]
	s_setprio 0
	s_barrier
	ds_read_b128 v[36:39], v152 offset:16384
	ds_read_b128 v[44:47], v152 offset:17408
	ds_read_b128 v[52:55], v152 offset:18432
	ds_read_b128 v[56:59], v152 offset:19456
	ds_read_b128 v[60:63], v152 offset:20480
	ds_read_b128 v[88:91], v152 offset:21504
	ds_read_b128 v[96:99], v152 offset:22528
	ds_read_b128 v[104:107], v152 offset:23552
	s_mov_b32 m0, s51
	s_nop 0
	global_load_lds_dwordx4 v145, s[44:45]
	s_mov_b32 m0, s54
	s_nop 0
	global_load_lds_dwordx4 v147, s[44:45]
	s_add_u32 s44, s36, 0x41000
	s_addc_u32 s45, s37, 0
	s_mov_b32 m0, s55
	s_nop 0
	global_load_lds_dwordx4 v145, s[44:45]
	s_mov_b32 m0, s58
	s_nop 0
	global_load_lds_dwordx4 v147, s[44:45]
	s_mov_b32 m0, s48
	s_nop 0
	global_load_lds_dwordx4 v144, s[38:39]
	s_mov_b32 m0, s59
	s_nop 0
	global_load_lds_dwordx4 v146, s[38:39]
	s_waitcnt vmcnt(8)
	s_waitcnt lgkmcnt(0)
	s_barrier
	s_setprio 1
	s_waitcnt lgkmcnt(7)
	v_mfma_f32_16x16x32_bf16 v[160:163], v[0:3], v[36:39], 0
	v_mfma_f32_16x16x32_bf16 v[168:171], v[8:11], v[36:39], 0
	s_waitcnt lgkmcnt(5)
	v_mfma_f32_16x16x32_bf16 v[172:175], v[0:3], v[52:55], 0
	v_mfma_f32_16x16x32_bf16 v[176:179], v[8:11], v[52:55], 0
	s_waitcnt lgkmcnt(3)
	v_mfma_f32_16x16x32_bf16 v[180:183], v[0:3], v[60:63], 0
	v_mfma_f32_16x16x32_bf16 v[184:187], v[8:11], v[60:63], 0
	s_waitcnt lgkmcnt(1)
	v_mfma_f32_16x16x32_bf16 v[188:191], v[0:3], v[96:99], 0
	v_mfma_f32_16x16x32_bf16 v[0:3], v[8:11], v[96:99], 0
	v_mfma_f32_16x16x32_bf16 v[160:163], v[4:7], v[44:47], v[160:163]
	v_mfma_f32_16x16x32_bf16 v[168:171], v[12:15], v[44:47], v[168:171]
	v_mfma_f32_16x16x32_bf16 v[172:175], v[4:7], v[56:59], v[172:175]
	v_mfma_f32_16x16x32_bf16 v[176:179], v[12:15], v[56:59], v[176:179]
	v_mfma_f32_16x16x32_bf16 v[180:183], v[4:7], v[88:91], v[180:183]
	v_mfma_f32_16x16x32_bf16 v[184:187], v[12:15], v[88:91], v[184:187]
	s_waitcnt lgkmcnt(0)
	v_mfma_f32_16x16x32_bf16 v[188:191], v[4:7], v[104:107], v[188:191]
	v_mfma_f32_16x16x32_bf16 v[0:3], v[12:15], v[104:107], v[0:3]
	s_setprio 0
	s_setprio 1
	v_mfma_f32_16x16x32_bf16 v[4:7], v[16:19], v[36:39], 0
	v_mfma_f32_16x16x32_bf16 v[12:15], v[24:27], v[36:39], 0
	v_mfma_f32_16x16x32_bf16 v[36:39], v[16:19], v[52:55], 0
	v_mfma_f32_16x16x32_bf16 v[192:195], v[24:27], v[52:55], 0
	v_mfma_f32_16x16x32_bf16 v[196:199], v[16:19], v[60:63], 0
	v_mfma_f32_16x16x32_bf16 v[200:203], v[24:27], v[60:63], 0
	v_mfma_f32_16x16x32_bf16 v[204:207], v[16:19], v[96:99], 0
	v_mfma_f32_16x16x32_bf16 v[208:211], v[24:27], v[96:99], 0
	s_nop 0
	v_mfma_f32_16x16x32_bf16 v[4:7], v[20:23], v[44:47], v[4:7]
	v_mfma_f32_16x16x32_bf16 v[12:15], v[28:31], v[44:47], v[12:15]
	v_mfma_f32_16x16x32_bf16 v[36:39], v[20:23], v[56:59], v[36:39]
	v_mfma_f32_16x16x32_bf16 v[192:195], v[28:31], v[56:59], v[192:195]
	v_mfma_f32_16x16x32_bf16 v[196:199], v[20:23], v[88:91], v[196:199]
	v_mfma_f32_16x16x32_bf16 v[200:203], v[28:31], v[88:91], v[200:203]
	v_mfma_f32_16x16x32_bf16 v[204:207], v[20:23], v[104:107], v[204:207]
	v_mfma_f32_16x16x32_bf16 v[208:211], v[28:31], v[104:107], v[208:211]
	s_setprio 0
	s_barrier
	ds_read_b128 v[8:11], v153
	ds_read_b128 v[20:23], v153 offset:1024
	ds_read_b128 v[28:31], v153 offset:2048
	ds_read_b128 v[44:47], v153 offset:3072
	ds_read_b128 v[212:215], v154
	ds_read_b128 v[216:219], v154 offset:1024
	ds_read_b128 v[220:223], v154 offset:2048
	ds_read_b128 v[224:227], v154 offset:3072
	ds_read_b128 v[16:19], v152 offset:32768
	ds_read_b128 v[24:27], v152 offset:33792
	ds_read_b128 v[52:55], v152 offset:34816
	ds_read_b128 v[56:59], v152 offset:35840
	ds_read_b128 v[228:231], v152 offset:36864
	ds_read_b128 v[232:235], v152 offset:37888
	ds_read_b128 v[236:239], v152 offset:38912
	ds_read_b128 v[240:243], v152 offset:39936
	s_add_u32 s40, s40, 0x41000
	s_addc_u32 s41, s41, 0
	s_mov_b32 m0, s60
	s_nop 0
	global_load_lds_dwordx4 v144, s[40:41]
	s_mov_b32 m0, s61
	s_nop 0
	global_load_lds_dwordx4 v146, s[40:41]
	s_waitcnt vmcnt(8)
	s_waitcnt lgkmcnt(0)
	s_barrier
	s_setprio 1
	s_waitcnt lgkmcnt(7)
	v_mfma_f32_16x16x32_bf16 v[60:63], v[8:11], v[16:19], v[64:67]
	s_waitcnt lgkmcnt(6)
	v_mfma_f32_16x16x32_bf16 v[120:123], v[20:23], v[24:27], v[60:63]
	v_mfma_f32_16x16x32_bf16 v[60:63], v[28:31], v[16:19], v[68:71]
	v_mfma_f32_16x16x32_bf16 v[112:115], v[44:47], v[24:27], v[60:63]
	s_waitcnt lgkmcnt(5)
	v_mfma_f32_16x16x32_bf16 v[60:63], v[8:11], v[52:55], v[72:75]
	s_waitcnt lgkmcnt(4)
	v_mfma_f32_16x16x32_bf16 v[104:107], v[20:23], v[56:59], v[60:63]
	v_mfma_f32_16x16x32_bf16 v[60:63], v[28:31], v[52:55], v[76:79]
	v_mfma_f32_16x16x32_bf16 v[96:99], v[44:47], v[56:59], v[60:63]
	s_waitcnt lgkmcnt(3)
	v_mfma_f32_16x16x32_bf16 v[60:63], v[8:11], v[228:231], v[80:83]
	s_waitcnt lgkmcnt(2)
	v_mfma_f32_16x16x32_bf16 v[88:91], v[20:23], v[232:235], v[60:63]
	v_mfma_f32_16x16x32_bf16 v[60:63], v[28:31], v[228:231], v[84:87]
	v_mfma_f32_16x16x32_bf16 v[80:83], v[44:47], v[232:235], v[60:63]
	s_waitcnt lgkmcnt(1)
	v_mfma_f32_16x16x32_bf16 v[60:63], v[8:11], v[236:239], v[92:95]
	s_waitcnt lgkmcnt(0)
	v_mfma_f32_16x16x32_bf16 v[72:75], v[20:23], v[240:243], v[60:63]
	v_mfma_f32_16x16x32_bf16 v[60:63], v[28:31], v[236:239], v[100:103]
	v_mfma_f32_16x16x32_bf16 v[60:63], v[44:47], v[240:243], v[60:63]
	s_setprio 0
	s_setprio 1
	v_mfma_f32_16x16x32_bf16 v[64:67], v[212:215], v[16:19], v[108:111]
	v_mfma_f32_16x16x32_bf16 v[16:19], v[220:223], v[16:19], v[116:119]
	v_mfma_f32_16x16x32_bf16 v[116:119], v[224:227], v[24:27], v[16:19]
	v_mfma_f32_16x16x32_bf16 v[16:19], v[212:215], v[52:55], v[32:35]
	v_mfma_f32_16x16x32_bf16 v[108:111], v[216:219], v[56:59], v[16:19]
	v_mfma_f32_16x16x32_bf16 v[16:19], v[220:223], v[52:55], v[136:139]
	v_mfma_f32_16x16x32_bf16 v[100:103], v[224:227], v[56:59], v[16:19]
	v_mfma_f32_16x16x32_bf16 v[16:19], v[212:215], v[228:231], v[40:43]
	v_mfma_f32_16x16x32_bf16 v[92:95], v[216:219], v[232:235], v[16:19]
	v_mfma_f32_16x16x32_bf16 v[16:19], v[220:223], v[228:231], v[140:143]
	v_mfma_f32_16x16x32_bf16 v[84:87], v[224:227], v[232:235], v[16:19]
	v_mfma_f32_16x16x32_bf16 v[16:19], v[212:215], v[236:239], v[48:51]
	v_mfma_f32_16x16x32_bf16 v[76:79], v[216:219], v[240:243], v[16:19]
	v_mfma_f32_16x16x32_bf16 v[16:19], v[220:223], v[236:239], v[156:159]
	v_mfma_f32_16x16x32_bf16 v[124:127], v[216:219], v[24:27], v[64:67]
	v_mfma_f32_16x16x32_bf16 v[64:67], v[224:227], v[240:243], v[16:19]
	s_setprio 0
	s_barrier
; #define PG8_ITER(F8) PG8_ITER_X(F8, false)
; #define PG8_ITER_FIRST(F8) PG8_ITER_X(F8, true)
;     ...
;         int t = 0;
;         if constexpr (NT8 > 0) { const int nt8 = NT8 < nt ? NT8 : nt;
;             { PG8_ITER_FIRST(true) } t = 2;
;             _Pragma("nounroll") for (; t < nt8; t += 2) PG8_ITER(true)
;             if constexpr (NT8 < ALL8) asm volatile("s_nop 15\n\ts_nop 15" ::: "memory"); }
;         if constexpr (NT8 < ALL8) {
;             if constexpr (NT8 == 0) { { PG8_ITER_FIRST(false) } t = 2; }
;             _Pragma("nounroll") for (; t < nt; t += 2) PG8_ITER(false) }
	ds_read_b128 v[52:55], v152 offset:49152
	ds_read_b128 v[136:139], v152 offset:50176
	ds_read_b128 v[140:143], v152 offset:51200
	ds_read_b128 v[156:159], v152 offset:52224
	ds_read_b128 v[228:231], v152 offset:53248
	ds_read_b128 v[232:235], v152 offset:54272
	ds_read_b128 v[236:239], v152 offset:55296
	ds_read_b128 v[240:243], v152 offset:56320
	s_add_u32 s40, s36, 0x1800
	s_addc_u32 s41, s37, 0
	s_mov_b32 m0, s65
	s_nop 0
	global_load_lds_dwordx4 v145, s[40:41]
	s_mov_b32 m0, s66
	s_nop 0
	global_load_lds_dwordx4 v147, s[40:41]
	s_add_u32 s40, s36, 0x41800
	s_addc_u32 s41, s37, 0
	s_mov_b32 m0, s69
	s_nop 0
	global_load_lds_dwordx4 v145, s[40:41]
	s_mov_b32 m0, s70
	s_nop 0
	global_load_lds_dwordx4 v147, s[40:41]
	s_mov_b32 m0, s67
	s_nop 0
	global_load_lds_dwordx4 v144, s[42:43]
	s_mov_b32 m0, s68
	s_nop 0
	global_load_lds_dwordx4 v146, s[42:43]
	s_waitcnt vmcnt(8)
	s_waitcnt lgkmcnt(0)
	s_barrier
	s_setprio 1
	s_waitcnt lgkmcnt(7)
	v_mfma_f32_16x16x32_bf16 v[16:19], v[8:11], v[52:55], v[160:163]
	s_waitcnt lgkmcnt(6)
	v_mfma_f32_16x16x32_bf16 v[56:59], v[20:23], v[136:139], v[16:19]
	v_mfma_f32_16x16x32_bf16 v[16:19], v[28:31], v[52:55], v[168:171]
	v_mfma_f32_16x16x32_bf16 v[48:51], v[44:47], v[136:139], v[16:19]
	s_waitcnt lgkmcnt(5)
	v_mfma_f32_16x16x32_bf16 v[16:19], v[8:11], v[140:143], v[172:175]
	s_waitcnt lgkmcnt(4)
	v_mfma_f32_16x16x32_bf16 v[40:43], v[20:23], v[156:159], v[16:19]
	v_mfma_f32_16x16x32_bf16 v[16:19], v[28:31], v[140:143], v[176:179]
	v_mfma_f32_16x16x32_bf16 v[32:35], v[44:47], v[156:159], v[16:19]
	s_waitcnt lgkmcnt(3)
	v_mfma_f32_16x16x32_bf16 v[16:19], v[8:11], v[228:231], v[180:183]
	s_waitcnt lgkmcnt(2)
	v_mfma_f32_16x16x32_bf16 v[24:27], v[20:23], v[232:235], v[16:19]
	v_mfma_f32_16x16x32_bf16 v[16:19], v[28:31], v[228:231], v[184:187]
	s_waitcnt lgkmcnt(1)
	v_mfma_f32_16x16x32_bf16 v[8:11], v[8:11], v[236:239], v[188:191]
	v_mfma_f32_16x16x32_bf16 v[0:3], v[28:31], v[236:239], v[0:3]
	v_mfma_f32_16x16x32_bf16 v[16:19], v[44:47], v[232:235], v[16:19]
	s_waitcnt lgkmcnt(0)
	v_mfma_f32_16x16x32_bf16 v[8:11], v[20:23], v[240:243], v[8:11]
	v_mfma_f32_16x16x32_bf16 v[0:3], v[44:47], v[240:243], v[0:3]
	s_setprio 0
	s_setprio 1
	v_mfma_f32_16x16x32_bf16 v[4:7], v[212:215], v[52:55], v[4:7]
	v_mfma_f32_16x16x32_bf16 v[68:71], v[216:219], v[136:139], v[4:7]
	v_mfma_f32_16x16x32_bf16 v[4:7], v[220:223], v[52:55], v[12:15]
	v_mfma_f32_16x16x32_bf16 v[52:55], v[224:227], v[136:139], v[4:7]
	v_mfma_f32_16x16x32_bf16 v[4:7], v[212:215], v[140:143], v[36:39]
	v_mfma_f32_16x16x32_bf16 v[44:47], v[216:219], v[156:159], v[4:7]
	v_mfma_f32_16x16x32_bf16 v[4:7], v[220:223], v[140:143], v[192:195]
	v_mfma_f32_16x16x32_bf16 v[36:39], v[224:227], v[156:159], v[4:7]
	v_mfma_f32_16x16x32_bf16 v[4:7], v[212:215], v[228:231], v[196:199]
	v_mfma_f32_16x16x32_bf16 v[28:31], v[216:219], v[232:235], v[4:7]
	v_mfma_f32_16x16x32_bf16 v[4:7], v[220:223], v[228:231], v[200:203]
	v_mfma_f32_16x16x32_bf16 v[20:23], v[224:227], v[232:235], v[4:7]
	v_mfma_f32_16x16x32_bf16 v[4:7], v[212:215], v[236:239], v[204:207]
	v_mfma_f32_16x16x32_bf16 v[12:15], v[216:219], v[240:243], v[4:7]
	v_mfma_f32_16x16x32_bf16 v[4:7], v[220:223], v[236:239], v[208:211]
	v_mfma_f32_16x16x32_bf16 v[4:7], v[224:227], v[240:243], v[4:7]
	s_setprio 0
	s_waitcnt vmcnt(6)
	s_barrier
	s_lshl_b32 s22, s22, 8
	s_ashr_i32 s23, s22, 31
	v_lshl_add_u64 v[136:137], s[22:23], 2, v[130:131]
	s_add_u32 s23, s36, 0x2000
	s_addc_u32 s77, s37, 0
	s_mov_b32 s78, 0
	ds_read_b128 v[188:191], v152
	ds_read_b128 v[192:195], v152 offset:1024
	ds_read_b128 v[196:199], v152 offset:2048
	ds_read_b128 v[200:203], v152 offset:3072
	ds_read_b128 v[204:207], v152 offset:4096
	ds_read_b128 v[208:211], v152 offset:5120
	ds_read_b128 v[212:215], v152 offset:6144
	ds_read_b128 v[216:219], v152 offset:7168

.LBB0_487:
	ds_read_b128 v[138:141], v150
	ds_read_b128 v[156:159], v150 offset:1024
	ds_read_b128 v[160:163], v150 offset:2048
	ds_read_b128 v[168:171], v150 offset:3072
	ds_read_b128 v[172:175], v151
	ds_read_b128 v[176:179], v151 offset:1024
	ds_read_b128 v[180:183], v151 offset:2048
	ds_read_b128 v[184:187], v151 offset:3072
	s_add_u32 s36, s38, 0x1000
	s_addc_u32 s37, s39, 0
	s_and_b64 s[40:41], s[40:41], exec
	s_cselect_b32 s46, s11, s36
	s_cselect_b32 s47, s1, s37
	s_cselect_b32 s41, s17, s77
	s_cselect_b32 s40, s76, s23
	s_add_u32 s42, s46, 0x800
	s_addc_u32 s43, s47, 0
	s_add_u32 s44, s40, 0x800
	s_addc_u32 s45, s41, 0
	s_add_u32 s38, s38, 0x40800
	s_addc_u32 s39, s39, 0
	s_mov_b32 m0, s71
	s_nop 0
	global_load_lds_dwordx4 v144, s[38:39]
	s_mov_b32 m0, s72
	s_nop 0
	global_load_lds_dwordx4 v146, s[38:39]
	s_waitcnt vmcnt(8)
	s_waitcnt lgkmcnt(0)
	s_barrier
	s_setprio 1
	v_mfma_f32_16x16x32_bf16 v[120:123], v[138:141], v[188:191], v[120:123]
	v_mfma_f32_16x16x32_bf16 v[112:115], v[160:163], v[188:191], v[112:115]
	ds_read_b128 v[220:223], v152 offset:16384
	v_mfma_f32_16x16x32_bf16 v[104:107], v[138:141], v[196:199], v[104:107]
	v_mfma_f32_16x16x32_bf16 v[96:99], v[160:163], v[196:199], v[96:99]
	v_mfma_f32_16x16x32_bf16 v[88:91], v[138:141], v[204:207], v[88:91]
	v_mfma_f32_16x16x32_bf16 v[80:83], v[160:163], v[204:207], v[80:83]
	ds_read_b128 v[224:227], v152 offset:17408
	v_mfma_f32_16x16x32_bf16 v[72:75], v[138:141], v[212:215], v[72:75]
	v_mfma_f32_16x16x32_bf16 v[60:63], v[160:163], v[212:215], v[60:63]
	v_mfma_f32_16x16x32_bf16 v[120:123], v[156:159], v[192:195], v[120:123]
	v_mfma_f32_16x16x32_bf16 v[112:115], v[168:171], v[192:195], v[112:115]
	ds_read_b128 v[228:231], v152 offset:18432
	v_mfma_f32_16x16x32_bf16 v[104:107], v[156:159], v[200:203], v[104:107]
	v_mfma_f32_16x16x32_bf16 v[96:99], v[168:171], v[200:203], v[96:99]
	v_mfma_f32_16x16x32_bf16 v[88:91], v[156:159], v[208:211], v[88:91]
	v_mfma_f32_16x16x32_bf16 v[80:83], v[168:171], v[208:211], v[80:83]
	ds_read_b128 v[232:235], v152 offset:19456
	v_mfma_f32_16x16x32_bf16 v[72:75], v[156:159], v[216:219], v[72:75]
	v_mfma_f32_16x16x32_bf16 v[60:63], v[168:171], v[216:219], v[60:63]
	s_setprio 0
	s_setprio 1
	v_mfma_f32_16x16x32_bf16 v[124:127], v[172:175], v[188:191], v[124:127]
	v_mfma_f32_16x16x32_bf16 v[116:119], v[180:183], v[188:191], v[116:119]
	ds_read_b128 v[236:239], v152 offset:20480
	v_mfma_f32_16x16x32_bf16 v[108:111], v[172:175], v[196:199], v[108:111]
	v_mfma_f32_16x16x32_bf16 v[100:103], v[180:183], v[196:199], v[100:103]
	v_mfma_f32_16x16x32_bf16 v[92:95], v[172:175], v[204:207], v[92:95]
	v_mfma_f32_16x16x32_bf16 v[84:87], v[180:183], v[204:207], v[84:87]
	ds_read_b128 v[240:243], v152 offset:21504
	v_mfma_f32_16x16x32_bf16 v[76:79], v[172:175], v[212:215], v[76:79]
	v_mfma_f32_16x16x32_bf16 v[64:67], v[180:183], v[212:215], v[64:67]
	v_mfma_f32_16x16x32_bf16 v[124:127], v[176:179], v[192:195], v[124:127]
	v_mfma_f32_16x16x32_bf16 v[116:119], v[184:187], v[192:195], v[116:119]
	ds_read_b128 v[244:247], v152 offset:22528
	v_mfma_f32_16x16x32_bf16 v[108:111], v[176:179], v[200:203], v[108:111]
	v_mfma_f32_16x16x32_bf16 v[100:103], v[184:187], v[200:203], v[100:103]
	v_mfma_f32_16x16x32_bf16 v[92:95], v[176:179], v[208:211], v[92:95]
	v_mfma_f32_16x16x32_bf16 v[84:87], v[184:187], v[208:211], v[84:87]
	ds_read_b128 v[248:251], v152 offset:23552
	v_mfma_f32_16x16x32_bf16 v[76:79], v[176:179], v[216:219], v[76:79]
	v_mfma_f32_16x16x32_bf16 v[64:67], v[184:187], v[216:219], v[64:67]
	s_setprio 0
	s_waitcnt vmcnt(2)
	s_barrier
	s_mov_b32 m0, s51
	s_nop 0
	global_load_lds_dwordx4 v145, s[40:41]
	s_mov_b32 m0, s54
	s_nop 0
	global_load_lds_dwordx4 v147, s[40:41]
	s_add_u32 s38, s40, 0x40000
	s_addc_u32 s39, s41, 0
	s_mov_b32 m0, s55
	s_nop 0
	global_load_lds_dwordx4 v145, s[38:39]
	s_mov_b32 m0, s58
	s_nop 0
	global_load_lds_dwordx4 v147, s[38:39]
	s_mov_b32 m0, s48
	s_nop 0
	global_load_lds_dwordx4 v144, s[46:47]
	s_mov_b32 m0, s59
	s_nop 0
	global_load_lds_dwordx4 v146, s[46:47]
	s_waitcnt vmcnt(8)
	s_waitcnt lgkmcnt(0)
	s_barrier
	s_setprio 1
	v_mfma_f32_16x16x32_bf16 v[56:59], v[138:141], v[220:223], v[56:59]
	v_mfma_f32_16x16x32_bf16 v[48:51], v[160:163], v[220:223], v[48:51]
	ds_read_b128 v[188:191], v152 offset:32768
	v_mfma_f32_16x16x32_bf16 v[40:43], v[138:141], v[228:231], v[40:43]
	v_mfma_f32_16x16x32_bf16 v[32:35], v[160:163], v[228:231], v[32:35]
	v_mfma_f32_16x16x32_bf16 v[24:27], v[138:141], v[236:239], v[24:27]
	v_mfma_f32_16x16x32_bf16 v[16:19], v[160:163], v[236:239], v[16:19]
	ds_read_b128 v[192:195], v152 offset:33792
	v_mfma_f32_16x16x32_bf16 v[8:11], v[138:141], v[244:247], v[8:11]
	v_mfma_f32_16x16x32_bf16 v[0:3], v[160:163], v[244:247], v[0:3]
	v_mfma_f32_16x16x32_bf16 v[56:59], v[156:159], v[224:227], v[56:59]
	v_mfma_f32_16x16x32_bf16 v[48:51], v[168:171], v[224:227], v[48:51]
	ds_read_b128 v[196:199], v152 offset:34816
	v_mfma_f32_16x16x32_bf16 v[40:43], v[156:159], v[232:235], v[40:43]
	v_mfma_f32_16x16x32_bf16 v[32:35], v[168:171], v[232:235], v[32:35]
	v_mfma_f32_16x16x32_bf16 v[24:27], v[156:159], v[240:243], v[24:27]
	v_mfma_f32_16x16x32_bf16 v[16:19], v[168:171], v[240:243], v[16:19]
	ds_read_b128 v[200:203], v152 offset:35840
	v_mfma_f32_16x16x32_bf16 v[8:11], v[156:159], v[248:251], v[8:11]
	v_mfma_f32_16x16x32_bf16 v[0:3], v[168:171], v[248:251], v[0:3]
	s_setprio 0
	s_setprio 1
	v_mfma_f32_16x16x32_bf16 v[68:71], v[172:175], v[220:223], v[68:71]
	v_mfma_f32_16x16x32_bf16 v[52:55], v[180:183], v[220:223], v[52:55]
	ds_read_b128 v[204:207], v152 offset:36864
	v_mfma_f32_16x16x32_bf16 v[44:47], v[172:175], v[228:231], v[44:47]
	v_mfma_f32_16x16x32_bf16 v[36:39], v[180:183], v[228:231], v[36:39]
	v_mfma_f32_16x16x32_bf16 v[28:31], v[172:175], v[236:239], v[28:31]
	v_mfma_f32_16x16x32_bf16 v[20:23], v[180:183], v[236:239], v[20:23]
	ds_read_b128 v[208:211], v152 offset:37888
	v_mfma_f32_16x16x32_bf16 v[12:15], v[172:175], v[244:247], v[12:15]
	v_mfma_f32_16x16x32_bf16 v[4:7], v[180:183], v[244:247], v[4:7]
	v_mfma_f32_16x16x32_bf16 v[68:71], v[176:179], v[224:227], v[68:71]
	v_mfma_f32_16x16x32_bf16 v[52:55], v[184:187], v[224:227], v[52:55]
	ds_read_b128 v[212:215], v152 offset:38912
	v_mfma_f32_16x16x32_bf16 v[44:47], v[176:179], v[232:235], v[44:47]
	v_mfma_f32_16x16x32_bf16 v[36:39], v[184:187], v[232:235], v[36:39]
	v_mfma_f32_16x16x32_bf16 v[28:31], v[176:179], v[240:243], v[28:31]
	v_mfma_f32_16x16x32_bf16 v[20:23], v[184:187], v[240:243], v[20:23]
	ds_read_b128 v[216:219], v152 offset:39936
	v_mfma_f32_16x16x32_bf16 v[12:15], v[176:179], v[248:251], v[12:15]
	v_mfma_f32_16x16x32_bf16 v[4:7], v[184:187], v[248:251], v[4:7]
	s_setprio 0
	s_waitcnt vmcnt(6)
	s_barrier
	ds_read_b128 v[138:141], v153
	ds_read_b128 v[156:159], v153 offset:1024
	ds_read_b128 v[160:163], v153 offset:2048
	ds_read_b128 v[168:171], v153 offset:3072
	ds_read_b128 v[172:175], v154
	ds_read_b128 v[176:179], v154 offset:1024
	ds_read_b128 v[180:183], v154 offset:2048
	ds_read_b128 v[184:187], v154 offset:3072
	s_add_u32 s38, s46, 0x40000
	s_addc_u32 s39, s47, 0
	s_mov_b32 m0, s60
	s_nop 0
	global_load_lds_dwordx4 v144, s[38:39]
	s_mov_b32 m0, s61
	s_nop 0
	global_load_lds_dwordx4 v146, s[38:39]
	s_waitcnt vmcnt(8)
	s_waitcnt lgkmcnt(0)
	s_barrier
	s_setprio 1
	v_mfma_f32_16x16x32_bf16 v[120:123], v[138:141], v[188:191], v[120:123]
	v_mfma_f32_16x16x32_bf16 v[112:115], v[160:163], v[188:191], v[112:115]
	ds_read_b128 v[220:223], v152 offset:49152
	v_mfma_f32_16x16x32_bf16 v[104:107], v[138:141], v[196:199], v[104:107]
	v_mfma_f32_16x16x32_bf16 v[96:99], v[160:163], v[196:199], v[96:99]
	v_mfma_f32_16x16x32_bf16 v[88:91], v[138:141], v[204:207], v[88:91]
	v_mfma_f32_16x16x32_bf16 v[80:83], v[160:163], v[204:207], v[80:83]
	ds_read_b128 v[224:227], v152 offset:50176
	v_mfma_f32_16x16x32_bf16 v[72:75], v[138:141], v[212:215], v[72:75]
	v_mfma_f32_16x16x32_bf16 v[60:63], v[160:163], v[212:215], v[60:63]
	v_mfma_f32_16x16x32_bf16 v[120:123], v[156:159], v[192:195], v[120:123]
	v_mfma_f32_16x16x32_bf16 v[112:115], v[168:171], v[192:195], v[112:115]
	ds_read_b128 v[228:231], v152 offset:51200
	v_mfma_f32_16x16x32_bf16 v[104:107], v[156:159], v[200:203], v[104:107]
	v_mfma_f32_16x16x32_bf16 v[96:99], v[168:171], v[200:203], v[96:99]
	v_mfma_f32_16x16x32_bf16 v[88:91], v[156:159], v[208:211], v[88:91]
	v_mfma_f32_16x16x32_bf16 v[80:83], v[168:171], v[208:211], v[80:83]
	ds_read_b128 v[232:235], v152 offset:52224
	v_mfma_f32_16x16x32_bf16 v[72:75], v[156:159], v[216:219], v[72:75]
	v_mfma_f32_16x16x32_bf16 v[60:63], v[168:171], v[216:219], v[60:63]
	s_setprio 0
	s_setprio 1
	v_mfma_f32_16x16x32_bf16 v[124:127], v[172:175], v[188:191], v[124:127]
	v_mfma_f32_16x16x32_bf16 v[116:119], v[180:183], v[188:191], v[116:119]
	ds_read_b128 v[236:239], v152 offset:53248
	v_mfma_f32_16x16x32_bf16 v[108:111], v[172:175], v[196:199], v[108:111]
	v_mfma_f32_16x16x32_bf16 v[100:103], v[180:183], v[196:199], v[100:103]
	v_mfma_f32_16x16x32_bf16 v[92:95], v[172:175], v[204:207], v[92:95]
	v_mfma_f32_16x16x32_bf16 v[84:87], v[180:183], v[204:207], v[84:87]
	ds_read_b128 v[240:243], v152 offset:54272
	v_mfma_f32_16x16x32_bf16 v[76:79], v[172:175], v[212:215], v[76:79]
	v_mfma_f32_16x16x32_bf16 v[64:67], v[180:183], v[212:215], v[64:67]
	v_mfma_f32_16x16x32_bf16 v[124:127], v[176:179], v[192:195], v[124:127]
	v_mfma_f32_16x16x32_bf16 v[116:119], v[184:187], v[192:195], v[116:119]
	ds_read_b128 v[244:247], v152 offset:55296
	v_mfma_f32_16x16x32_bf16 v[108:111], v[176:179], v[200:203], v[108:111]
	v_mfma_f32_16x16x32_bf16 v[100:103], v[184:187], v[200:203], v[100:103]
	v_mfma_f32_16x16x32_bf16 v[92:95], v[176:179], v[208:211], v[92:95]
	v_mfma_f32_16x16x32_bf16 v[84:87], v[184:187], v[208:211], v[84:87]
	ds_read_b128 v[248:251], v152 offset:56320
	v_mfma_f32_16x16x32_bf16 v[76:79], v[176:179], v[216:219], v[76:79]
	v_mfma_f32_16x16x32_bf16 v[64:67], v[184:187], v[216:219], v[64:67]
	s_setprio 0
	s_waitcnt vmcnt(2)
	s_barrier
	s_mov_b32 m0, s65
	s_nop 0
	global_load_lds_dwordx4 v145, s[44:45]
	s_mov_b32 m0, s66
	s_nop 0
	global_load_lds_dwordx4 v147, s[44:45]
	s_add_u32 s38, s40, 0x40800
	s_addc_u32 s39, s41, 0
	s_mov_b32 m0, s69
	s_nop 0
	global_load_lds_dwordx4 v145, s[38:39]
	s_mov_b32 m0, s70
	s_nop 0
	global_load_lds_dwordx4 v147, s[38:39]
	s_mov_b32 m0, s67
	s_nop 0
	global_load_lds_dwordx4 v144, s[42:43]
	s_mov_b32 m0, s68
	s_nop 0
	global_load_lds_dwordx4 v146, s[42:43]
	s_waitcnt vmcnt(8)
	s_waitcnt lgkmcnt(0)
	s_barrier
	s_setprio 1
	v_mfma_f32_16x16x32_bf16 v[56:59], v[138:141], v[220:223], v[56:59]
	v_mfma_f32_16x16x32_bf16 v[48:51], v[160:163], v[220:223], v[48:51]
	ds_read_b128 v[188:191], v152
	v_mfma_f32_16x16x32_bf16 v[40:43], v[138:141], v[228:231], v[40:43]
	v_mfma_f32_16x16x32_bf16 v[32:35], v[160:163], v[228:231], v[32:35]
	v_mfma_f32_16x16x32_bf16 v[24:27], v[138:141], v[236:239], v[24:27]
	v_mfma_f32_16x16x32_bf16 v[16:19], v[160:163], v[236:239], v[16:19]
	ds_read_b128 v[192:195], v152 offset:1024
	v_mfma_f32_16x16x32_bf16 v[8:11], v[138:141], v[244:247], v[8:11]
	v_mfma_f32_16x16x32_bf16 v[0:3], v[160:163], v[244:247], v[0:3]
	v_mfma_f32_16x16x32_bf16 v[56:59], v[156:159], v[224:227], v[56:59]
	v_mfma_f32_16x16x32_bf16 v[48:51], v[168:171], v[224:227], v[48:51]
	ds_read_b128 v[196:199], v152 offset:2048
	v_mfma_f32_16x16x32_bf16 v[40:43], v[156:159], v[232:235], v[40:43]
	v_mfma_f32_16x16x32_bf16 v[32:35], v[168:171], v[232:235], v[32:35]
	v_mfma_f32_16x16x32_bf16 v[24:27], v[156:159], v[240:243], v[24:27]
	v_mfma_f32_16x16x32_bf16 v[16:19], v[168:171], v[240:243], v[16:19]
	ds_read_b128 v[200:203], v152 offset:3072
	v_mfma_f32_16x16x32_bf16 v[8:11], v[156:159], v[248:251], v[8:11]
	v_mfma_f32_16x16x32_bf16 v[0:3], v[168:171], v[248:251], v[0:3]
	s_setprio 0
	s_setprio 1
	v_mfma_f32_16x16x32_bf16 v[68:71], v[172:175], v[220:223], v[68:71]
	v_mfma_f32_16x16x32_bf16 v[52:55], v[180:183], v[220:223], v[52:55]
	ds_read_b128 v[204:207], v152 offset:4096
	v_mfma_f32_16x16x32_bf16 v[44:47], v[172:175], v[228:231], v[44:47]
	v_mfma_f32_16x16x32_bf16 v[36:39], v[180:183], v[228:231], v[36:39]
	v_mfma_f32_16x16x32_bf16 v[28:31], v[172:175], v[236:239], v[28:31]
	v_mfma_f32_16x16x32_bf16 v[20:23], v[180:183], v[236:239], v[20:23]
	ds_read_b128 v[208:211], v152 offset:5120
	v_mfma_f32_16x16x32_bf16 v[12:15], v[172:175], v[244:247], v[12:15]
	v_mfma_f32_16x16x32_bf16 v[4:7], v[180:183], v[244:247], v[4:7]
	v_mfma_f32_16x16x32_bf16 v[68:71], v[176:179], v[224:227], v[68:71]
	v_mfma_f32_16x16x32_bf16 v[52:55], v[184:187], v[224:227], v[52:55]
	ds_read_b128 v[212:215], v152 offset:6144
	v_mfma_f32_16x16x32_bf16 v[44:47], v[176:179], v[232:235], v[44:47]
	v_mfma_f32_16x16x32_bf16 v[36:39], v[184:187], v[232:235], v[36:39]
	v_mfma_f32_16x16x32_bf16 v[28:31], v[176:179], v[240:243], v[28:31]
	v_mfma_f32_16x16x32_bf16 v[20:23], v[184:187], v[240:243], v[20:23]
	ds_read_b128 v[216:219], v152 offset:7168
	v_mfma_f32_16x16x32_bf16 v[12:15], v[176:179], v[248:251], v[12:15]
	v_mfma_f32_16x16x32_bf16 v[4:7], v[184:187], v[248:251], v[4:7]
	s_setprio 0
	s_waitcnt vmcnt(6)
	s_barrier
	s_add_i32 s78, s78, 2
	s_add_u32 s23, s23, 0x1000
	s_addc_u32 s77, s77, 0
	s_cmp_lt_u32 s78, 14
	s_cbranch_scc0 .LBB0_489
	s_mov_b64 s[38:39], s[36:37]
	s_branch .LBB0_485

; __global__ void __launch_bounds__(NWAVES * 64, 2) fwd_megakernel(Args args) {
	.amdhsa_kernel _Z14fwd_megakernel4Args
		.amdhsa_group_segment_fixed_size 0
		.amdhsa_private_segment_fixed_size 0
		.amdhsa_kernarg_size 392
		.amdhsa_user_sgpr_count 2
		.amdhsa_user_sgpr_dispatch_ptr 0
		.amdhsa_user_sgpr_queue_ptr 0
		.amdhsa_user_sgpr_kernarg_segment_ptr 1
		.amdhsa_user_sgpr_dispatch_id 0
		.amdhsa_user_sgpr_kernarg_preload_length 0
		.amdhsa_user_sgpr_kernarg_preload_offset 0
		.amdhsa_user_sgpr_private_segment_size 0
		.amdhsa_uses_dynamic_stack 0
		.amdhsa_enable_private_segment 0
		.amdhsa_system_sgpr_workgroup_id_x 1
		.amdhsa_system_sgpr_workgroup_id_y 0
		.amdhsa_system_sgpr_workgroup_id_z 0
		.amdhsa_system_sgpr_workgroup_info 0
		.amdhsa_system_vgpr_workitem_id 0
		.amdhsa_next_free_vgpr 256
		.amdhsa_next_free_sgpr 102
		.amdhsa_accum_offset 256
		.amdhsa_reserve_vcc 1
		.amdhsa_float_round_mode_32 0
		.amdhsa_float_round_mode_16_64 0
		.amdhsa_float_denorm_mode_32 3
		.amdhsa_float_denorm_mode_16_64 3
		.amdhsa_dx10_clamp 1
		.amdhsa_ieee_mode 1
		.amdhsa_fp16_overflow 0
		.amdhsa_tg_split 0
		.amdhsa_exception_fp_ieee_invalid_op 0
		.amdhsa_exception_fp_denorm_src 0
		.amdhsa_exception_fp_ieee_div_zero 0
		.amdhsa_exception_fp_ieee_overflow 0
		.amdhsa_exception_fp_ieee_underflow 0
		.amdhsa_exception_fp_ieee_inexact 0
		.amdhsa_exception_int_div_zero 0
	.end_amdhsa_kernel

; __global__ void __launch_bounds__(NWAVES * 64, 2) fwd_megakernel(Args args) {
amdhsa.kernels:
  - .agpr_count:     0
    .args:
      - .offset:         0
        .size:           136
        .value_kind:     by_value
      - .offset:         136
        .size:           4
        .value_kind:     hidden_block_count_x
      - .offset:         140
        .size:           4
        .value_kind:     hidden_block_count_y
      - .offset:         144
        .size:           4
        .value_kind:     hidden_block_count_z
      - .offset:         148
        .size:           2
        .value_kind:     hidden_group_size_x
      - .offset:         150
        .size:           2
        .value_kind:     hidden_group_size_y
      - .offset:         152
        .size:           2
        .value_kind:     hidden_group_size_z
      - .offset:         154
        .size:           2
        .value_kind:     hidden_remainder_x
      - .offset:         156
        .size:           2
        .value_kind:     hidden_remainder_y
      - .offset:         158
        .size:           2
        .value_kind:     hidden_remainder_z
      - .offset:         176
        .size:           8
        .value_kind:     hidden_global_offset_x
      - .offset:         184
        .size:           8
        .value_kind:     hidden_global_offset_y
      - .offset:         192
        .size:           8
        .value_kind:     hidden_global_offset_z
      - .offset:         200
        .size:           2
        .value_kind:     hidden_grid_dims
      - .offset:         256
        .size:           4
        .value_kind:     hidden_dynamic_lds_size
    .group_segment_fixed_size: 0
    .kernarg_segment_align: 8
    .kernarg_segment_size: 392
    .language:       OpenCL C
    .language_version:
      - 2
      - 0
    .max_flat_workgroup_size: 512
    .name:           _Z14fwd_megakernel4Args
    .private_segment_fixed_size: 0
    .sgpr_count:     108
    .sgpr_spill_count: 4
    .symbol:         _Z14fwd_megakernel4Args.kd
    .uniform_work_group_size: 1
    .uses_dynamic_stack: false
    .vgpr_count:     256
    .vgpr_spill_count: 0
    .wavefront_size: 64
